# A tiles: unclamped rel-bias path with immediate-offset ds_read2_b32 (no per-element index math) when the whole tile is inside the table
# speedup vs baseline: 1.0073x; 1.0073x over previous
.LBB0_722:
	s_andn2_b64 vcc, exec, s[16:17]
	s_cbranch_vccnz .LBB0_724
	v_or_b32_e32 v0, s18, v159
	v_sub_u32_e32 v62, v226, v0
	v_cmp_gt_u32_e32 vcc, 59, v62
	s_cbranch_vccnz .Lmy_slow_a
	v_cmp_lt_u32_e32 vcc, 256, v62
	s_cbranch_vccnz .Lmy_slow_a
	v_lshl_add_u32 v0, v62, 2, s91
	v_add_u32_e32 v0, 0xffffff14, v0
	ds_read2_b32 v[34:35], v0 offset0:59 offset1:58
	ds_read2_b32 v[38:39], v0 offset0:57 offset1:56
	ds_read2_b32 v[42:43], v0 offset0:51 offset1:50
	ds_read2_b32 v[46:47], v0 offset0:49 offset1:48
	ds_read2_b32 v[50:51], v0 offset0:43 offset1:42
	ds_read2_b32 v[54:55], v0 offset0:41 offset1:40
	ds_read2_b32 v[56:57], v0 offset0:35 offset1:34
	ds_read2_b32 v[62:63], v0 offset0:33 offset1:32
	ds_read2_b32 v[36:37], v0 offset0:27 offset1:26
	ds_read2_b32 v[40:41], v0 offset0:25 offset1:24
	ds_read2_b32 v[44:45], v0 offset0:19 offset1:18
	ds_read2_b32 v[48:49], v0 offset0:17 offset1:16
	ds_read2_b32 v[52:53], v0 offset0:11 offset1:10
	ds_read2_b32 v[60:61], v0 offset0:9 offset1:8
	ds_read2_b32 v[58:59], v0 offset0:3 offset1:2
	s_waitcnt lgkmcnt(14)
	v_pk_fma_f32 v[34:35], v[18:19], s[68:69], v[34:35] op_sel_hi:[1,0,1]
	ds_read2_b32 v[64:65], v0 offset0:1 offset1:0
	s_waitcnt lgkmcnt(14)
	v_pk_fma_f32 v[38:39], v[20:21], s[68:69], v[38:39] op_sel_hi:[1,0,1]
	s_waitcnt lgkmcnt(13)
	v_pk_fma_f32 v[42:43], v[22:23], s[68:69], v[42:43] op_sel_hi:[1,0,1]
	s_waitcnt lgkmcnt(12)
	v_pk_fma_f32 v[46:47], v[24:25], s[68:69], v[46:47] op_sel_hi:[1,0,1]
	s_waitcnt lgkmcnt(11)
	v_pk_fma_f32 v[50:51], v[26:27], s[68:69], v[50:51] op_sel_hi:[1,0,1]
	s_waitcnt lgkmcnt(10)
	v_pk_fma_f32 v[54:55], v[28:29], s[68:69], v[54:55] op_sel_hi:[1,0,1]
	s_waitcnt lgkmcnt(9)
	v_pk_fma_f32 v[56:57], v[30:31], s[68:69], v[56:57] op_sel_hi:[1,0,1]
	s_waitcnt lgkmcnt(8)
	v_pk_fma_f32 v[62:63], v[32:33], s[68:69], v[62:63] op_sel_hi:[1,0,1]
	s_waitcnt lgkmcnt(7)
	v_pk_fma_f32 v[36:37], v[2:3], s[68:69], v[36:37] op_sel_hi:[1,0,1]
	s_waitcnt lgkmcnt(6)
	v_pk_fma_f32 v[40:41], v[4:5], s[68:69], v[40:41] op_sel_hi:[1,0,1]
	s_waitcnt lgkmcnt(5)
	v_pk_fma_f32 v[44:45], v[6:7], s[68:69], v[44:45] op_sel_hi:[1,0,1]
	s_waitcnt lgkmcnt(4)
	v_pk_fma_f32 v[48:49], v[8:9], s[68:69], v[48:49] op_sel_hi:[1,0,1]
	s_waitcnt lgkmcnt(3)
	v_pk_fma_f32 v[52:53], v[10:11], s[68:69], v[52:53] op_sel_hi:[1,0,1]
	s_waitcnt lgkmcnt(2)
	v_pk_fma_f32 v[60:61], v[12:13], s[68:69], v[60:61] op_sel_hi:[1,0,1]
	s_waitcnt lgkmcnt(1)
	v_pk_fma_f32 v[58:59], v[14:15], s[68:69], v[58:59] op_sel_hi:[1,0,1]
	s_waitcnt lgkmcnt(0)
	v_pk_fma_f32 v[64:65], v[16:17], s[68:69], v[64:65] op_sel_hi:[1,0,1]
	s_branch .LBB0_724
.Lmy_slow_a:
	v_med3_i32 v35, v62, 32, v202
	v_med3_i32 v34, v62, 0, v201
	v_lshl_add_u32 v35, v35, 2, s91
	v_lshl_add_u32 v34, v34, 2, s91
	v_add_u32_e32 v35, 0xffffff80, v35
	v_xad_u32 v0, v0, -1, v226
	ds_read_b32 v34, v34
	ds_read_b32 v36, v35
	v_med3_i32 v35, v0, 0, v201
	v_med3_i32 v0, v0, 32, v202
	v_lshl_add_u32 v0, v0, 2, s91
	v_add_u32_e32 v0, 0xffffff80, v0
	ds_read_b32 v37, v0
	v_lshl_add_u32 v35, v35, 2, s91
	ds_read_b32 v35, v35
	v_add_u32_e32 v0, -2, v62
	s_waitcnt lgkmcnt(1)
	v_pk_fma_f32 v[36:37], v[2:3], s[68:69], v[36:37] op_sel_hi:[1,0,1]
	v_med3_i32 v2, v0, 0, v201
	v_med3_i32 v0, v0, 32, v202
	v_lshl_add_u32 v0, v0, 2, s91
	v_lshl_add_u32 v2, v2, 2, s91
	v_add_u32_e32 v0, 0xffffff80, v0
	ds_read_b32 v2, v2
	s_waitcnt lgkmcnt(1)
	v_pk_fma_f32 v[34:35], v[18:19], s[68:69], v[34:35] op_sel_hi:[1,0,1]
	ds_read_b32 v18, v0
	v_add_u32_e32 v0, -3, v62
	v_med3_i32 v3, v0, 0, v201
	v_lshl_add_u32 v3, v3, 2, s91
	v_med3_i32 v0, v0, 32, v202
	ds_read_b32 v3, v3
	v_lshl_add_u32 v0, v0, 2, s91
	v_add_u32_e32 v0, 0xffffff80, v0
	ds_read_b32 v19, v0
	v_add_u32_e32 v0, -8, v62
	s_waitcnt lgkmcnt(1)
	v_pk_fma_f32 v[38:39], v[20:21], s[68:69], v[2:3] op_sel_hi:[1,0,1]
	v_med3_i32 v2, v0, 0, v201
	v_med3_i32 v0, v0, 32, v202
	v_lshl_add_u32 v0, v0, 2, s91
	v_lshl_add_u32 v2, v2, 2, s91
	v_add_u32_e32 v0, 0xffffff80, v0
	s_waitcnt lgkmcnt(0)
	v_pk_fma_f32 v[40:41], v[4:5], s[68:69], v[18:19] op_sel_hi:[1,0,1]
	ds_read_b32 v2, v2
	ds_read_b32 v4, v0
	v_add_u32_e32 v0, -9, v62
	v_med3_i32 v3, v0, 0, v201
	v_lshl_add_u32 v3, v3, 2, s91
	v_med3_i32 v0, v0, 32, v202
	ds_read_b32 v3, v3
	v_lshl_add_u32 v0, v0, 2, s91
	v_add_u32_e32 v0, 0xffffff80, v0
	ds_read_b32 v5, v0
	v_add_u32_e32 v0, -10, v62
	s_waitcnt lgkmcnt(1)
	v_pk_fma_f32 v[42:43], v[22:23], s[68:69], v[2:3] op_sel_hi:[1,0,1]
	v_med3_i32 v2, v0, 0, v201
	v_med3_i32 v0, v0, 32, v202
	v_lshl_add_u32 v0, v0, 2, s91
	v_lshl_add_u32 v2, v2, 2, s91
	v_add_u32_e32 v0, 0xffffff80, v0
	s_waitcnt lgkmcnt(0)
	v_pk_fma_f32 v[44:45], v[6:7], s[68:69], v[4:5] op_sel_hi:[1,0,1]
	ds_read_b32 v2, v2
	ds_read_b32 v4, v0
	v_add_u32_e32 v0, -11, v62
	v_med3_i32 v3, v0, 0, v201
	v_lshl_add_u32 v3, v3, 2, s91
	v_med3_i32 v0, v0, 32, v202
	ds_read_b32 v3, v3
	v_lshl_add_u32 v0, v0, 2, s91
	v_add_u32_e32 v0, 0xffffff80, v0
	ds_read_b32 v5, v0
	v_add_u32_e32 v0, -16, v62
	s_waitcnt lgkmcnt(1)
	v_pk_fma_f32 v[46:47], v[24:25], s[68:69], v[2:3] op_sel_hi:[1,0,1]
	v_med3_i32 v2, v0, 0, v201
	v_med3_i32 v0, v0, 32, v202
	v_lshl_add_u32 v0, v0, 2, s91
	v_lshl_add_u32 v2, v2, 2, s91
	v_add_u32_e32 v0, 0xffffff80, v0
	s_waitcnt lgkmcnt(0)
	v_pk_fma_f32 v[48:49], v[8:9], s[68:69], v[4:5] op_sel_hi:[1,0,1]
	ds_read_b32 v2, v2
	ds_read_b32 v4, v0
	v_subrev_u32_e32 v0, 17, v62
	v_med3_i32 v3, v0, 0, v201
	v_lshl_add_u32 v3, v3, 2, s91
	v_med3_i32 v0, v0, 32, v202
	ds_read_b32 v3, v3
	v_lshl_add_u32 v0, v0, 2, s91
	v_add_u32_e32 v0, 0xffffff80, v0
	ds_read_b32 v5, v0
	v_subrev_u32_e32 v0, 18, v62
	s_waitcnt lgkmcnt(1)
	v_pk_fma_f32 v[50:51], v[26:27], s[68:69], v[2:3] op_sel_hi:[1,0,1]
	v_med3_i32 v2, v0, 0, v201
	v_med3_i32 v0, v0, 32, v202
	v_lshl_add_u32 v0, v0, 2, s91
	v_lshl_add_u32 v2, v2, 2, s91
	v_add_u32_e32 v0, 0xffffff80, v0
	s_waitcnt lgkmcnt(0)
	v_pk_fma_f32 v[52:53], v[10:11], s[68:69], v[4:5] op_sel_hi:[1,0,1]
	ds_read_b32 v2, v2
	ds_read_b32 v4, v0
	v_subrev_u32_e32 v0, 19, v62
	v_med3_i32 v3, v0, 0, v201
	v_lshl_add_u32 v3, v3, 2, s91
	v_med3_i32 v0, v0, 32, v202
	ds_read_b32 v3, v3
	v_lshl_add_u32 v0, v0, 2, s91
	v_add_u32_e32 v0, 0xffffff80, v0
	ds_read_b32 v5, v0
	v_subrev_u32_e32 v0, 24, v62
	s_waitcnt lgkmcnt(1)
	v_pk_fma_f32 v[54:55], v[28:29], s[68:69], v[2:3] op_sel_hi:[1,0,1]
	v_med3_i32 v2, v0, 0, v201
	v_med3_i32 v0, v0, 32, v202
	v_lshl_add_u32 v0, v0, 2, s91
	v_lshl_add_u32 v2, v2, 2, s91
	v_add_u32_e32 v0, 0xffffff80, v0
	s_waitcnt lgkmcnt(0)
	v_pk_fma_f32 v[60:61], v[12:13], s[68:69], v[4:5] op_sel_hi:[1,0,1]
	ds_read_b32 v2, v2
	ds_read_b32 v4, v0
	v_subrev_u32_e32 v0, 25, v62
	v_med3_i32 v3, v0, 0, v201
	v_lshl_add_u32 v3, v3, 2, s91
	v_med3_i32 v0, v0, 32, v202
	ds_read_b32 v3, v3
	v_lshl_add_u32 v0, v0, 2, s91
	v_add_u32_e32 v0, 0xffffff80, v0
	ds_read_b32 v5, v0
	v_subrev_u32_e32 v0, 26, v62
	s_waitcnt lgkmcnt(1)
	v_pk_fma_f32 v[56:57], v[30:31], s[68:69], v[2:3] op_sel_hi:[1,0,1]
	v_med3_i32 v2, v0, 0, v201
	v_med3_i32 v0, v0, 32, v202
	v_lshl_add_u32 v0, v0, 2, s91
	v_lshl_add_u32 v2, v2, 2, s91
	v_add_u32_e32 v0, 0xffffff80, v0
	s_waitcnt lgkmcnt(0)
	v_pk_fma_f32 v[58:59], v[14:15], s[68:69], v[4:5] op_sel_hi:[1,0,1]
	ds_read_b32 v2, v2
	ds_read_b32 v4, v0
	v_subrev_u32_e32 v0, 27, v62
	v_med3_i32 v3, v0, 0, v201
	v_med3_i32 v0, v0, 32, v202
	v_lshl_add_u32 v0, v0, 2, s91
	v_lshl_add_u32 v3, v3, 2, s91
	v_add_u32_e32 v0, 0xffffff80, v0
	ds_read_b32 v3, v3
	ds_read_b32 v5, v0
	s_waitcnt lgkmcnt(1)
	v_pk_fma_f32 v[62:63], v[32:33], s[68:69], v[2:3] op_sel_hi:[1,0,1]
	s_waitcnt lgkmcnt(0)
	v_pk_fma_f32 v[64:65], v[16:17], s[68:69], v[4:5] op_sel_hi:[1,0,1]

.LBB0_742:
	s_andn2_b64 vcc, exec, s[16:17]
	s_cbranch_vccnz .LBB0_744
	v_or_b32_e32 v0, s3, v159
	v_sub_u32_e32 v151, v226, v0
	v_cmp_gt_u32_e32 vcc, 59, v151
	s_cbranch_vccnz .Lmy_slow_b
	v_cmp_lt_u32_e32 vcc, 256, v151
	s_cbranch_vccnz .Lmy_slow_b
	v_lshl_add_u32 v0, v151, 2, s91
	v_add_u32_e32 v0, 0xffffff14, v0
	ds_read2_b32 v[2:3], v0 offset0:59 offset1:58
	ds_read2_b32 v[6:7], v0 offset0:57 offset1:56
	ds_read2_b32 v[10:11], v0 offset0:51 offset1:50
	ds_read2_b32 v[14:15], v0 offset0:49 offset1:48
	ds_read2_b32 v[178:179], v0 offset0:43 offset1:42
	ds_read2_b32 v[182:183], v0 offset0:41 offset1:40
	ds_read2_b32 v[186:187], v0 offset0:35 offset1:34
	ds_read2_b32 v[190:191], v0 offset0:33 offset1:32
	ds_read2_b32 v[4:5], v0 offset0:27 offset1:26
	ds_read2_b32 v[8:9], v0 offset0:25 offset1:24
	ds_read2_b32 v[12:13], v0 offset0:19 offset1:18
	ds_read2_b32 v[176:177], v0 offset0:17 offset1:16
	ds_read2_b32 v[180:181], v0 offset0:11 offset1:10
	ds_read2_b32 v[184:185], v0 offset0:9 offset1:8
	ds_read2_b32 v[188:189], v0 offset0:3 offset1:2
	s_waitcnt lgkmcnt(14)
	v_pk_fma_f32 v[2:3], v[64:65], s[68:69], v[2:3] op_sel_hi:[1,0,1]
	ds_read2_b32 v[192:193], v0 offset0:1 offset1:0
	s_waitcnt lgkmcnt(14)
	v_pk_fma_f32 v[6:7], v[66:67], s[68:69], v[6:7] op_sel_hi:[1,0,1]
	s_waitcnt lgkmcnt(13)
	v_pk_fma_f32 v[10:11], v[68:69], s[68:69], v[10:11] op_sel_hi:[1,0,1]
	s_waitcnt lgkmcnt(12)
	v_pk_fma_f32 v[14:15], v[70:71], s[68:69], v[14:15] op_sel_hi:[1,0,1]
	s_waitcnt lgkmcnt(11)
	v_pk_fma_f32 v[178:179], v[72:73], s[68:69], v[178:179] op_sel_hi:[1,0,1]
	s_waitcnt lgkmcnt(10)
	v_pk_fma_f32 v[182:183], v[74:75], s[68:69], v[182:183] op_sel_hi:[1,0,1]
	s_waitcnt lgkmcnt(9)
	v_pk_fma_f32 v[186:187], v[76:77], s[68:69], v[186:187] op_sel_hi:[1,0,1]
	s_waitcnt lgkmcnt(8)
	v_pk_fma_f32 v[190:191], v[78:79], s[68:69], v[190:191] op_sel_hi:[1,0,1]
	s_waitcnt lgkmcnt(7)
	v_pk_fma_f32 v[4:5], v[48:49], s[68:69], v[4:5] op_sel_hi:[1,0,1]
	s_waitcnt lgkmcnt(6)
	v_pk_fma_f32 v[8:9], v[50:51], s[68:69], v[8:9] op_sel_hi:[1,0,1]
	s_waitcnt lgkmcnt(5)
	v_pk_fma_f32 v[12:13], v[52:53], s[68:69], v[12:13] op_sel_hi:[1,0,1]
	s_waitcnt lgkmcnt(4)
	v_pk_fma_f32 v[176:177], v[54:55], s[68:69], v[176:177] op_sel_hi:[1,0,1]
	s_waitcnt lgkmcnt(3)
	v_pk_fma_f32 v[180:181], v[56:57], s[68:69], v[180:181] op_sel_hi:[1,0,1]
	s_waitcnt lgkmcnt(2)
	v_pk_fma_f32 v[184:185], v[58:59], s[68:69], v[184:185] op_sel_hi:[1,0,1]
	s_waitcnt lgkmcnt(1)
	v_pk_fma_f32 v[188:189], v[60:61], s[68:69], v[188:189] op_sel_hi:[1,0,1]
	s_waitcnt lgkmcnt(0)
	v_pk_fma_f32 v[192:193], v[62:63], s[68:69], v[192:193] op_sel_hi:[1,0,1]
	s_branch .LBB0_744
.Lmy_slow_b:
	v_med3_i32 v3, v151, 32, v202
	v_med3_i32 v2, v151, 0, v201
	v_lshl_add_u32 v3, v3, 2, s91
	v_lshl_add_u32 v2, v2, 2, s91
	v_add_u32_e32 v3, 0xffffff80, v3
	v_xad_u32 v0, v0, -1, v226
	ds_read_b32 v2, v2
	ds_read_b32 v4, v3
	v_med3_i32 v3, v0, 0, v201
	v_med3_i32 v0, v0, 32, v202
	v_lshl_add_u32 v0, v0, 2, s91
	v_add_u32_e32 v0, 0xffffff80, v0
	ds_read_b32 v5, v0
	v_add_u32_e32 v0, -2, v151
	v_med3_i32 v6, v0, 0, v201
	v_med3_i32 v0, v0, 32, v202
	v_lshl_add_u32 v0, v0, 2, s91
	v_lshl_add_u32 v3, v3, 2, s91
	v_add_u32_e32 v0, 0xffffff80, v0
	ds_read_b32 v3, v3
	ds_read_b32 v8, v0
	v_add_u32_e32 v0, -3, v151
	v_med3_i32 v7, v0, 0, v201
	v_med3_i32 v0, v0, 32, v202
	v_lshl_add_u32 v0, v0, 2, s91
	v_lshl_add_u32 v6, v6, 2, s91
	v_add_u32_e32 v0, 0xffffff80, v0
	ds_read_b32 v6, v6
	ds_read_b32 v9, v0
	v_add_u32_e32 v0, -8, v151
	v_med3_i32 v10, v0, 0, v201
	v_med3_i32 v0, v0, 32, v202
	v_lshl_add_u32 v0, v0, 2, s91
	v_lshl_add_u32 v7, v7, 2, s91
	v_add_u32_e32 v0, 0xffffff80, v0
	ds_read_b32 v7, v7
	ds_read_b32 v12, v0
	v_add_u32_e32 v0, -9, v151
	v_med3_i32 v11, v0, 0, v201
	v_med3_i32 v0, v0, 32, v202
	v_lshl_add_u32 v0, v0, 2, s91
	v_lshl_add_u32 v10, v10, 2, s91
	v_add_u32_e32 v0, 0xffffff80, v0
	ds_read_b32 v10, v10
	ds_read_b32 v13, v0
	v_add_u32_e32 v0, -10, v151
	v_med3_i32 v14, v0, 0, v201
	v_med3_i32 v0, v0, 32, v202
	v_lshl_add_u32 v0, v0, 2, s91
	v_lshl_add_u32 v11, v11, 2, s91
	v_add_u32_e32 v0, 0xffffff80, v0
	s_waitcnt lgkmcnt(8)
	v_pk_fma_f32 v[4:5], v[48:49], s[68:69], v[4:5] op_sel_hi:[1,0,1]
	ds_read_b32 v11, v11
	ds_read_b32 v48, v0
	v_add_u32_e32 v0, -11, v151
	v_med3_i32 v15, v0, 0, v201
	v_med3_i32 v0, v0, 32, v202
	v_lshl_add_u32 v0, v0, 2, s91
	v_lshl_add_u32 v14, v14, 2, s91
	v_add_u32_e32 v0, 0xffffff80, v0
	ds_read_b32 v14, v14
	ds_read_b32 v49, v0
	v_add_u32_e32 v0, -16, v151
	v_lshl_add_u32 v15, v15, 2, s91
	s_waitcnt lgkmcnt(8)
	v_pk_fma_f32 v[8:9], v[50:51], s[68:69], v[8:9] op_sel_hi:[1,0,1]
	ds_read_b32 v15, v15
	s_waitcnt lgkmcnt(1)
	v_pk_fma_f32 v[176:177], v[54:55], s[68:69], v[48:49] op_sel_hi:[1,0,1]
	v_med3_i32 v48, v0, 0, v201
	v_med3_i32 v0, v0, 32, v202
	v_lshl_add_u32 v0, v0, 2, s91
	v_add_u32_e32 v0, 0xffffff80, v0
	ds_read_b32 v50, v0
	v_subrev_u32_e32 v0, 17, v151
	v_med3_i32 v49, v0, 0, v201
	v_lshl_add_u32 v48, v48, 2, s91
	v_lshl_add_u32 v49, v49, 2, s91
	ds_read_b32 v48, v48
	ds_read_b32 v49, v49
	v_med3_i32 v0, v0, 32, v202
	v_lshl_add_u32 v0, v0, 2, s91
	v_add_u32_e32 v0, 0xffffff80, v0
	ds_read_b32 v51, v0
	v_subrev_u32_e32 v0, 18, v151
	s_waitcnt lgkmcnt(1)
	v_pk_fma_f32 v[178:179], v[72:73], s[68:69], v[48:49] op_sel_hi:[1,0,1]
	v_med3_i32 v48, v0, 0, v201
	v_med3_i32 v0, v0, 32, v202
	v_lshl_add_u32 v0, v0, 2, s91
	v_lshl_add_u32 v48, v48, 2, s91
	v_add_u32_e32 v0, 0xffffff80, v0
	s_waitcnt lgkmcnt(0)
	v_pk_fma_f32 v[180:181], v[56:57], s[68:69], v[50:51] op_sel_hi:[1,0,1]
	ds_read_b32 v48, v48
	ds_read_b32 v50, v0
	v_subrev_u32_e32 v0, 19, v151
	v_med3_i32 v49, v0, 0, v201
	v_lshl_add_u32 v49, v49, 2, s91
	v_med3_i32 v0, v0, 32, v202
	ds_read_b32 v49, v49
	v_lshl_add_u32 v0, v0, 2, s91
	v_add_u32_e32 v0, 0xffffff80, v0
	ds_read_b32 v51, v0
	v_subrev_u32_e32 v0, 24, v151
	s_waitcnt lgkmcnt(1)
	v_pk_fma_f32 v[182:183], v[74:75], s[68:69], v[48:49] op_sel_hi:[1,0,1]
	v_med3_i32 v48, v0, 0, v201
	v_med3_i32 v0, v0, 32, v202
	v_lshl_add_u32 v0, v0, 2, s91
	v_lshl_add_u32 v48, v48, 2, s91
	v_add_u32_e32 v0, 0xffffff80, v0
	s_waitcnt lgkmcnt(0)
	v_pk_fma_f32 v[184:185], v[58:59], s[68:69], v[50:51] op_sel_hi:[1,0,1]
	ds_read_b32 v48, v48
	ds_read_b32 v50, v0
	v_subrev_u32_e32 v0, 25, v151
	v_med3_i32 v49, v0, 0, v201
	v_lshl_add_u32 v49, v49, 2, s91
	v_med3_i32 v0, v0, 32, v202
	ds_read_b32 v49, v49
	v_lshl_add_u32 v0, v0, 2, s91
	v_add_u32_e32 v0, 0xffffff80, v0
	ds_read_b32 v51, v0
	v_subrev_u32_e32 v0, 26, v151
	s_waitcnt lgkmcnt(1)
	v_pk_fma_f32 v[186:187], v[76:77], s[68:69], v[48:49] op_sel_hi:[1,0,1]
	v_med3_i32 v48, v0, 0, v201
	v_med3_i32 v0, v0, 32, v202
	v_lshl_add_u32 v0, v0, 2, s91
	v_lshl_add_u32 v48, v48, 2, s91
	v_add_u32_e32 v0, 0xffffff80, v0
	s_waitcnt lgkmcnt(0)
	v_pk_fma_f32 v[188:189], v[60:61], s[68:69], v[50:51] op_sel_hi:[1,0,1]
	ds_read_b32 v48, v48
	ds_read_b32 v50, v0
	v_subrev_u32_e32 v0, 27, v151
	v_med3_i32 v49, v0, 0, v201
	v_med3_i32 v0, v0, 32, v202
	v_lshl_add_u32 v0, v0, 2, s91
	v_lshl_add_u32 v49, v49, 2, s91
	v_add_u32_e32 v0, 0xffffff80, v0
	ds_read_b32 v49, v49
	ds_read_b32 v51, v0
	v_pk_fma_f32 v[2:3], v[64:65], s[68:69], v[2:3] op_sel_hi:[1,0,1]
	v_pk_fma_f32 v[6:7], v[66:67], s[68:69], v[6:7] op_sel_hi:[1,0,1]
	v_pk_fma_f32 v[10:11], v[68:69], s[68:69], v[10:11] op_sel_hi:[1,0,1]
	v_pk_fma_f32 v[12:13], v[52:53], s[68:69], v[12:13] op_sel_hi:[1,0,1]
	v_pk_fma_f32 v[14:15], v[70:71], s[68:69], v[14:15] op_sel_hi:[1,0,1]
	s_waitcnt lgkmcnt(1)
	v_pk_fma_f32 v[190:191], v[78:79], s[68:69], v[48:49] op_sel_hi:[1,0,1]
	s_waitcnt lgkmcnt(0)
	v_pk_fma_f32 v[192:193], v[62:63], s[68:69], v[50:51] op_sel_hi:[1,0,1]

.LBB0_781:
	s_andn2_b64 vcc, exec, s[16:17]
	s_cbranch_vccnz .LBB0_783
	v_cmp_gt_u32_e32 vcc, 123, v226
	s_cbranch_vccnz .Lmy_slow_c
	v_cmp_lt_u32_e32 vcc, 320, v226
	s_cbranch_vccnz .Lmy_slow_c
	v_lshl_add_u32 v0, v226, 2, s91
	v_add_u32_e32 v0, 0xfffffe14, v0
	ds_read2_b32 v[2:3], v0 offset0:59 offset1:58
	ds_read2_b32 v[6:7], v0 offset0:57 offset1:56
	ds_read2_b32 v[10:11], v0 offset0:51 offset1:50
	ds_read2_b32 v[14:15], v0 offset0:49 offset1:48
	ds_read2_b32 v[178:179], v0 offset0:43 offset1:42
	ds_read2_b32 v[182:183], v0 offset0:41 offset1:40
	ds_read2_b32 v[186:187], v0 offset0:35 offset1:34
	ds_read2_b32 v[190:191], v0 offset0:33 offset1:32
	ds_read2_b32 v[4:5], v0 offset0:27 offset1:26
	ds_read2_b32 v[8:9], v0 offset0:25 offset1:24
	ds_read2_b32 v[12:13], v0 offset0:19 offset1:18
	ds_read2_b32 v[176:177], v0 offset0:17 offset1:16
	ds_read2_b32 v[180:181], v0 offset0:11 offset1:10
	ds_read2_b32 v[184:185], v0 offset0:9 offset1:8
	ds_read2_b32 v[188:189], v0 offset0:3 offset1:2
	s_waitcnt lgkmcnt(14)
	v_pk_fma_f32 v[2:3], v[64:65], s[68:69], v[2:3] op_sel_hi:[1,0,1]
	ds_read2_b32 v[192:193], v0 offset0:1 offset1:0
	s_waitcnt lgkmcnt(14)
	v_pk_fma_f32 v[6:7], v[66:67], s[68:69], v[6:7] op_sel_hi:[1,0,1]
	s_waitcnt lgkmcnt(13)
	v_pk_fma_f32 v[10:11], v[68:69], s[68:69], v[10:11] op_sel_hi:[1,0,1]
	s_waitcnt lgkmcnt(12)
	v_pk_fma_f32 v[14:15], v[70:71], s[68:69], v[14:15] op_sel_hi:[1,0,1]
	s_waitcnt lgkmcnt(11)
	v_pk_fma_f32 v[178:179], v[72:73], s[68:69], v[178:179] op_sel_hi:[1,0,1]
	s_waitcnt lgkmcnt(10)
	v_pk_fma_f32 v[182:183], v[74:75], s[68:69], v[182:183] op_sel_hi:[1,0,1]
	s_waitcnt lgkmcnt(9)
	v_pk_fma_f32 v[186:187], v[76:77], s[68:69], v[186:187] op_sel_hi:[1,0,1]
	s_waitcnt lgkmcnt(8)
	v_pk_fma_f32 v[190:191], v[78:79], s[68:69], v[190:191] op_sel_hi:[1,0,1]
	s_waitcnt lgkmcnt(7)
	v_pk_fma_f32 v[4:5], v[48:49], s[68:69], v[4:5] op_sel_hi:[1,0,1]
	s_waitcnt lgkmcnt(6)
	v_pk_fma_f32 v[8:9], v[50:51], s[68:69], v[8:9] op_sel_hi:[1,0,1]
	s_waitcnt lgkmcnt(5)
	v_pk_fma_f32 v[12:13], v[52:53], s[68:69], v[12:13] op_sel_hi:[1,0,1]
	s_waitcnt lgkmcnt(4)
	v_pk_fma_f32 v[176:177], v[54:55], s[68:69], v[176:177] op_sel_hi:[1,0,1]
	s_waitcnt lgkmcnt(3)
	v_pk_fma_f32 v[180:181], v[56:57], s[68:69], v[180:181] op_sel_hi:[1,0,1]
	s_waitcnt lgkmcnt(2)
	v_pk_fma_f32 v[184:185], v[58:59], s[68:69], v[184:185] op_sel_hi:[1,0,1]
	s_waitcnt lgkmcnt(1)
	v_pk_fma_f32 v[188:189], v[60:61], s[68:69], v[188:189] op_sel_hi:[1,0,1]
	s_waitcnt lgkmcnt(0)
	v_pk_fma_f32 v[192:193], v[62:63], s[68:69], v[192:193] op_sel_hi:[1,0,1]
	s_branch .LBB0_783
.Lmy_slow_c:
	v_subrev_u32_e32 v0, 64, v226
	v_med3_i32 v2, v0, 0, v201
	v_med3_i32 v0, v0, 32, v202
	v_lshl_add_u32 v0, v0, 2, s91
	v_lshl_add_u32 v2, v2, 2, s91
	v_add_u32_e32 v0, 0xffffff80, v0
	ds_read_b32 v2, v2
	ds_read_b32 v4, v0
	v_add_u32_e32 v0, 0xffffffbf, v226
	v_med3_i32 v3, v0, 0, v201
	v_med3_i32 v0, v0, 32, v202
	v_lshl_add_u32 v0, v0, 2, s91
	v_lshl_add_u32 v3, v3, 2, s91
	v_add_u32_e32 v0, 0xffffff80, v0
	ds_read_b32 v3, v3
	ds_read_b32 v5, v0
	v_add_u32_e32 v0, 0xffffffbe, v226
	v_med3_i32 v6, v0, 0, v201
	v_med3_i32 v0, v0, 32, v202
	v_lshl_add_u32 v0, v0, 2, s91
	v_lshl_add_u32 v6, v6, 2, s91
	v_add_u32_e32 v0, 0xffffff80, v0
	ds_read_b32 v6, v6
	ds_read_b32 v8, v0
	v_add_u32_e32 v0, 0xffffffbd, v226
	v_med3_i32 v7, v0, 0, v201
	v_med3_i32 v0, v0, 32, v202
	v_lshl_add_u32 v0, v0, 2, s91
	v_lshl_add_u32 v7, v7, 2, s91
	v_add_u32_e32 v0, 0xffffff80, v0
	ds_read_b32 v7, v7
	ds_read_b32 v9, v0
	v_add_u32_e32 v0, 0xffffffb8, v226
	v_med3_i32 v10, v0, 0, v201
	v_med3_i32 v0, v0, 32, v202
	v_lshl_add_u32 v0, v0, 2, s91
	v_lshl_add_u32 v10, v10, 2, s91
	v_add_u32_e32 v0, 0xffffff80, v0
	ds_read_b32 v10, v10
	ds_read_b32 v12, v0
	v_add_u32_e32 v0, 0xffffffb7, v226
	v_med3_i32 v11, v0, 0, v201
	v_med3_i32 v0, v0, 32, v202
	v_lshl_add_u32 v0, v0, 2, s91
	v_lshl_add_u32 v11, v11, 2, s91
	v_add_u32_e32 v0, 0xffffff80, v0
	ds_read_b32 v11, v11
	ds_read_b32 v13, v0
	v_add_u32_e32 v0, 0xffffffb6, v226
	v_med3_i32 v14, v0, 0, v201
	v_med3_i32 v0, v0, 32, v202
	v_lshl_add_u32 v0, v0, 2, s91
	v_lshl_add_u32 v14, v14, 2, s91
	v_add_u32_e32 v0, 0xffffff80, v0
	s_waitcnt lgkmcnt(8)
	v_pk_fma_f32 v[4:5], v[48:49], s[68:69], v[4:5] op_sel_hi:[1,0,1]
	ds_read_b32 v14, v14
	ds_read_b32 v48, v0
	v_add_u32_e32 v0, 0xffffffb5, v226
	v_med3_i32 v15, v0, 0, v201
	v_med3_i32 v0, v0, 32, v202
	v_lshl_add_u32 v0, v0, 2, s91
	v_lshl_add_u32 v15, v15, 2, s91
	v_add_u32_e32 v0, 0xffffff80, v0
	ds_read_b32 v15, v15
	ds_read_b32 v49, v0
	v_add_u32_e32 v0, 0xffffffb0, v226
	s_waitcnt lgkmcnt(8)
	v_pk_fma_f32 v[8:9], v[50:51], s[68:69], v[8:9] op_sel_hi:[1,0,1]
	v_pk_fma_f32 v[2:3], v[64:65], s[68:69], v[2:3] op_sel_hi:[1,0,1]
	v_pk_fma_f32 v[6:7], v[66:67], s[68:69], v[6:7] op_sel_hi:[1,0,1]
	s_waitcnt lgkmcnt(0)
	v_pk_fma_f32 v[176:177], v[54:55], s[68:69], v[48:49] op_sel_hi:[1,0,1]
	v_med3_i32 v48, v0, 0, v201
	v_med3_i32 v0, v0, 32, v202
	v_lshl_add_u32 v0, v0, 2, s91
	v_lshl_add_u32 v48, v48, 2, s91
	v_add_u32_e32 v0, 0xffffff80, v0
	ds_read_b32 v48, v48
	ds_read_b32 v50, v0
	v_add_u32_e32 v0, 0xffffffaf, v226
	v_med3_i32 v49, v0, 0, v201
	v_lshl_add_u32 v49, v49, 2, s91
	v_med3_i32 v0, v0, 32, v202
	ds_read_b32 v49, v49
	v_lshl_add_u32 v0, v0, 2, s91
	v_add_u32_e32 v0, 0xffffff80, v0
	ds_read_b32 v51, v0
	v_add_u32_e32 v0, 0xffffffae, v226
	s_waitcnt lgkmcnt(1)
	v_pk_fma_f32 v[178:179], v[72:73], s[68:69], v[48:49] op_sel_hi:[1,0,1]
	v_med3_i32 v48, v0, 0, v201
	v_med3_i32 v0, v0, 32, v202
	v_lshl_add_u32 v0, v0, 2, s91
	v_lshl_add_u32 v48, v48, 2, s91
	v_add_u32_e32 v0, 0xffffff80, v0
	s_waitcnt lgkmcnt(0)
	v_pk_fma_f32 v[180:181], v[56:57], s[68:69], v[50:51] op_sel_hi:[1,0,1]
	ds_read_b32 v48, v48
	ds_read_b32 v50, v0
	v_add_u32_e32 v0, 0xffffffad, v226
	v_med3_i32 v49, v0, 0, v201
	v_lshl_add_u32 v49, v49, 2, s91
	v_med3_i32 v0, v0, 32, v202
	ds_read_b32 v49, v49
	v_lshl_add_u32 v0, v0, 2, s91
	v_add_u32_e32 v0, 0xffffff80, v0
	ds_read_b32 v51, v0
	v_add_u32_e32 v0, 0xffffffa8, v226
	s_waitcnt lgkmcnt(1)
	v_pk_fma_f32 v[182:183], v[74:75], s[68:69], v[48:49] op_sel_hi:[1,0,1]
	v_med3_i32 v48, v0, 0, v201
	v_med3_i32 v0, v0, 32, v202
	v_lshl_add_u32 v0, v0, 2, s91
	v_lshl_add_u32 v48, v48, 2, s91
	v_add_u32_e32 v0, 0xffffff80, v0
	s_waitcnt lgkmcnt(0)
	v_pk_fma_f32 v[184:185], v[58:59], s[68:69], v[50:51] op_sel_hi:[1,0,1]
	ds_read_b32 v48, v48
	ds_read_b32 v50, v0
	v_add_u32_e32 v0, 0xffffffa7, v226
	v_med3_i32 v49, v0, 0, v201
	v_lshl_add_u32 v49, v49, 2, s91
	v_med3_i32 v0, v0, 32, v202
	ds_read_b32 v49, v49
	v_lshl_add_u32 v0, v0, 2, s91
	v_add_u32_e32 v0, 0xffffff80, v0
	ds_read_b32 v51, v0
	v_add_u32_e32 v0, 0xffffffa6, v226
	s_waitcnt lgkmcnt(1)
	v_pk_fma_f32 v[186:187], v[76:77], s[68:69], v[48:49] op_sel_hi:[1,0,1]
	v_med3_i32 v48, v0, 0, v201
	v_med3_i32 v0, v0, 32, v202
	v_lshl_add_u32 v0, v0, 2, s91
	v_lshl_add_u32 v48, v48, 2, s91
	v_add_u32_e32 v0, 0xffffff80, v0
	s_waitcnt lgkmcnt(0)
	v_pk_fma_f32 v[188:189], v[60:61], s[68:69], v[50:51] op_sel_hi:[1,0,1]
	ds_read_b32 v48, v48
	ds_read_b32 v50, v0
	v_add_u32_e32 v0, 0xffffffa5, v226
	v_med3_i32 v49, v0, 0, v201
	v_med3_i32 v0, v0, 32, v202
	v_lshl_add_u32 v0, v0, 2, s91
	v_lshl_add_u32 v49, v49, 2, s91
	v_add_u32_e32 v0, 0xffffff80, v0
	ds_read_b32 v49, v49
	ds_read_b32 v51, v0
	v_pk_fma_f32 v[10:11], v[68:69], s[68:69], v[10:11] op_sel_hi:[1,0,1]
	v_pk_fma_f32 v[12:13], v[52:53], s[68:69], v[12:13] op_sel_hi:[1,0,1]
	v_pk_fma_f32 v[14:15], v[70:71], s[68:69], v[14:15] op_sel_hi:[1,0,1]
	s_waitcnt lgkmcnt(1)
	v_pk_fma_f32 v[190:191], v[78:79], s[68:69], v[48:49] op_sel_hi:[1,0,1]
	s_waitcnt lgkmcnt(0)
	v_pk_fma_f32 v[192:193], v[62:63], s[68:69], v[50:51] op_sel_hi:[1,0,1]

.LBB0_794:
	s_andn2_b64 vcc, exec, s[16:17]
	s_cbranch_vccnz .LBB0_796
	v_cmp_gt_u32_e32 vcc, 59, v226
	s_cbranch_vccnz .Lmy_slow_d
	v_cmp_lt_u32_e32 vcc, 256, v226
	s_cbranch_vccnz .Lmy_slow_d
	v_lshl_add_u32 v0, v226, 2, s91
	v_add_u32_e32 v0, 0xffffff14, v0
	ds_read2_b32 v[2:3], v0 offset0:59 offset1:58
	ds_read2_b32 v[6:7], v0 offset0:57 offset1:56
	ds_read2_b32 v[10:11], v0 offset0:51 offset1:50
	ds_read2_b32 v[14:15], v0 offset0:49 offset1:48
	ds_read2_b32 v[178:179], v0 offset0:43 offset1:42
	ds_read2_b32 v[182:183], v0 offset0:41 offset1:40
	ds_read2_b32 v[186:187], v0 offset0:35 offset1:34
	ds_read2_b32 v[190:191], v0 offset0:33 offset1:32
	ds_read2_b32 v[4:5], v0 offset0:27 offset1:26
	ds_read2_b32 v[8:9], v0 offset0:25 offset1:24
	ds_read2_b32 v[12:13], v0 offset0:19 offset1:18
	ds_read2_b32 v[176:177], v0 offset0:17 offset1:16
	ds_read2_b32 v[180:181], v0 offset0:11 offset1:10
	ds_read2_b32 v[184:185], v0 offset0:9 offset1:8
	ds_read2_b32 v[188:189], v0 offset0:3 offset1:2
	s_waitcnt lgkmcnt(14)
	v_pk_fma_f32 v[2:3], v[64:65], s[68:69], v[2:3] op_sel_hi:[1,0,1]
	ds_read2_b32 v[192:193], v0 offset0:1 offset1:0
	s_waitcnt lgkmcnt(14)
	v_pk_fma_f32 v[6:7], v[66:67], s[68:69], v[6:7] op_sel_hi:[1,0,1]
	s_waitcnt lgkmcnt(13)
	v_pk_fma_f32 v[10:11], v[68:69], s[68:69], v[10:11] op_sel_hi:[1,0,1]
	s_waitcnt lgkmcnt(12)
	v_pk_fma_f32 v[14:15], v[70:71], s[68:69], v[14:15] op_sel_hi:[1,0,1]
	s_waitcnt lgkmcnt(11)
	v_pk_fma_f32 v[178:179], v[72:73], s[68:69], v[178:179] op_sel_hi:[1,0,1]
	s_waitcnt lgkmcnt(10)
	v_pk_fma_f32 v[182:183], v[74:75], s[68:69], v[182:183] op_sel_hi:[1,0,1]
	s_waitcnt lgkmcnt(9)
	v_pk_fma_f32 v[186:187], v[76:77], s[68:69], v[186:187] op_sel_hi:[1,0,1]
	s_waitcnt lgkmcnt(8)
	v_pk_fma_f32 v[190:191], v[78:79], s[68:69], v[190:191] op_sel_hi:[1,0,1]
	s_waitcnt lgkmcnt(7)
	v_pk_fma_f32 v[4:5], v[48:49], s[68:69], v[4:5] op_sel_hi:[1,0,1]
	s_waitcnt lgkmcnt(6)
	v_pk_fma_f32 v[8:9], v[50:51], s[68:69], v[8:9] op_sel_hi:[1,0,1]
	s_waitcnt lgkmcnt(5)
	v_pk_fma_f32 v[12:13], v[52:53], s[68:69], v[12:13] op_sel_hi:[1,0,1]
	s_waitcnt lgkmcnt(4)
	v_pk_fma_f32 v[176:177], v[54:55], s[68:69], v[176:177] op_sel_hi:[1,0,1]
	s_waitcnt lgkmcnt(3)
	v_pk_fma_f32 v[180:181], v[56:57], s[68:69], v[180:181] op_sel_hi:[1,0,1]
	s_waitcnt lgkmcnt(2)
	v_pk_fma_f32 v[184:185], v[58:59], s[68:69], v[184:185] op_sel_hi:[1,0,1]
	s_waitcnt lgkmcnt(1)
	v_pk_fma_f32 v[188:189], v[60:61], s[68:69], v[188:189] op_sel_hi:[1,0,1]
	s_waitcnt lgkmcnt(0)
	v_pk_fma_f32 v[192:193], v[62:63], s[68:69], v[192:193] op_sel_hi:[1,0,1]
	s_branch .LBB0_796
.Lmy_slow_d:
	v_med3_i32 v0, v226, 0, v201
	v_med3_i32 v3, v226, 32, v202
	v_lshl_add_u32 v0, v0, 2, s91
	ds_read_b32 v2, v0
	v_lshl_add_u32 v0, v3, 2, s91
	v_add_u32_e32 v0, 0xffffff80, v0
	ds_read_b32 v4, v0
	v_add_u32_e32 v0, -1, v226
	v_med3_i32 v3, v0, 0, v201
	v_med3_i32 v0, v0, 32, v202
	v_lshl_add_u32 v0, v0, 2, s91
	v_lshl_add_u32 v3, v3, 2, s91
	v_add_u32_e32 v0, 0xffffff80, v0
	ds_read_b32 v3, v3
	ds_read_b32 v5, v0
	v_add_u32_e32 v0, -2, v226
	v_med3_i32 v6, v0, 0, v201
	v_med3_i32 v0, v0, 32, v202
	v_lshl_add_u32 v0, v0, 2, s91
	v_lshl_add_u32 v6, v6, 2, s91
	v_add_u32_e32 v0, 0xffffff80, v0
	ds_read_b32 v6, v6
	ds_read_b32 v8, v0
	v_add_u32_e32 v0, -3, v226
	v_med3_i32 v7, v0, 0, v201
	v_med3_i32 v0, v0, 32, v202
	v_lshl_add_u32 v0, v0, 2, s91
	v_lshl_add_u32 v7, v7, 2, s91
	v_add_u32_e32 v0, 0xffffff80, v0
	ds_read_b32 v7, v7
	ds_read_b32 v9, v0
	v_add_u32_e32 v0, -8, v226
	v_med3_i32 v10, v0, 0, v201
	v_med3_i32 v0, v0, 32, v202
	v_lshl_add_u32 v0, v0, 2, s91
	v_lshl_add_u32 v10, v10, 2, s91
	v_add_u32_e32 v0, 0xffffff80, v0
	ds_read_b32 v10, v10
	ds_read_b32 v12, v0
	v_add_u32_e32 v0, -9, v226
	v_med3_i32 v11, v0, 0, v201
	v_med3_i32 v0, v0, 32, v202
	v_lshl_add_u32 v0, v0, 2, s91
	v_lshl_add_u32 v11, v11, 2, s91
	v_add_u32_e32 v0, 0xffffff80, v0
	ds_read_b32 v11, v11
	ds_read_b32 v13, v0
	v_add_u32_e32 v0, -10, v226
	v_med3_i32 v14, v0, 0, v201
	v_med3_i32 v0, v0, 32, v202
	v_lshl_add_u32 v0, v0, 2, s91
	v_lshl_add_u32 v14, v14, 2, s91
	v_add_u32_e32 v0, 0xffffff80, v0
	s_waitcnt lgkmcnt(8)
	v_pk_fma_f32 v[4:5], v[48:49], s[68:69], v[4:5] op_sel_hi:[1,0,1]
	ds_read_b32 v14, v14
	ds_read_b32 v48, v0
	v_add_u32_e32 v0, -11, v226
	v_med3_i32 v15, v0, 0, v201
	v_med3_i32 v0, v0, 32, v202
	v_lshl_add_u32 v0, v0, 2, s91
	v_lshl_add_u32 v15, v15, 2, s91
	v_add_u32_e32 v0, 0xffffff80, v0
	ds_read_b32 v15, v15
	ds_read_b32 v49, v0
	v_add_u32_e32 v0, -16, v226
	s_waitcnt lgkmcnt(8)
	v_pk_fma_f32 v[8:9], v[50:51], s[68:69], v[8:9] op_sel_hi:[1,0,1]
	v_pk_fma_f32 v[2:3], v[64:65], s[68:69], v[2:3] op_sel_hi:[1,0,1]
	v_pk_fma_f32 v[6:7], v[66:67], s[68:69], v[6:7] op_sel_hi:[1,0,1]
	s_waitcnt lgkmcnt(0)
	v_pk_fma_f32 v[176:177], v[54:55], s[68:69], v[48:49] op_sel_hi:[1,0,1]
	v_med3_i32 v48, v0, 0, v201
	v_med3_i32 v0, v0, 32, v202
	v_lshl_add_u32 v0, v0, 2, s91
	v_lshl_add_u32 v48, v48, 2, s91
	v_add_u32_e32 v0, 0xffffff80, v0
	ds_read_b32 v48, v48
	ds_read_b32 v50, v0
	v_subrev_u32_e32 v0, 17, v226
	v_med3_i32 v49, v0, 0, v201
	v_lshl_add_u32 v49, v49, 2, s91
	v_med3_i32 v0, v0, 32, v202
	ds_read_b32 v49, v49
	v_lshl_add_u32 v0, v0, 2, s91
	v_add_u32_e32 v0, 0xffffff80, v0
	ds_read_b32 v51, v0
	v_subrev_u32_e32 v0, 18, v226
	s_waitcnt lgkmcnt(1)
	v_pk_fma_f32 v[178:179], v[72:73], s[68:69], v[48:49] op_sel_hi:[1,0,1]
	v_med3_i32 v48, v0, 0, v201
	v_med3_i32 v0, v0, 32, v202
	v_lshl_add_u32 v0, v0, 2, s91
	v_lshl_add_u32 v48, v48, 2, s91
	v_add_u32_e32 v0, 0xffffff80, v0
	s_waitcnt lgkmcnt(0)
	v_pk_fma_f32 v[180:181], v[56:57], s[68:69], v[50:51] op_sel_hi:[1,0,1]
	ds_read_b32 v48, v48
	ds_read_b32 v50, v0
	v_subrev_u32_e32 v0, 19, v226
	v_med3_i32 v49, v0, 0, v201
	v_lshl_add_u32 v49, v49, 2, s91
	v_med3_i32 v0, v0, 32, v202
	ds_read_b32 v49, v49
	v_lshl_add_u32 v0, v0, 2, s91
	v_add_u32_e32 v0, 0xffffff80, v0
	ds_read_b32 v51, v0
	v_subrev_u32_e32 v0, 24, v226
	s_waitcnt lgkmcnt(1)
	v_pk_fma_f32 v[182:183], v[74:75], s[68:69], v[48:49] op_sel_hi:[1,0,1]
	v_med3_i32 v48, v0, 0, v201
	v_med3_i32 v0, v0, 32, v202
	v_lshl_add_u32 v0, v0, 2, s91
	v_lshl_add_u32 v48, v48, 2, s91
	v_add_u32_e32 v0, 0xffffff80, v0
	s_waitcnt lgkmcnt(0)
	v_pk_fma_f32 v[184:185], v[58:59], s[68:69], v[50:51] op_sel_hi:[1,0,1]
	ds_read_b32 v48, v48
	ds_read_b32 v50, v0
	v_subrev_u32_e32 v0, 25, v226
	v_med3_i32 v49, v0, 0, v201
	v_lshl_add_u32 v49, v49, 2, s91
	v_med3_i32 v0, v0, 32, v202
	ds_read_b32 v49, v49
	v_lshl_add_u32 v0, v0, 2, s91
	v_add_u32_e32 v0, 0xffffff80, v0
	ds_read_b32 v51, v0
	v_subrev_u32_e32 v0, 26, v226
	s_waitcnt lgkmcnt(1)
	v_pk_fma_f32 v[186:187], v[76:77], s[68:69], v[48:49] op_sel_hi:[1,0,1]
	v_med3_i32 v48, v0, 0, v201
	v_med3_i32 v0, v0, 32, v202
	v_lshl_add_u32 v0, v0, 2, s91
	v_lshl_add_u32 v48, v48, 2, s91
	v_add_u32_e32 v0, 0xffffff80, v0
	s_waitcnt lgkmcnt(0)
	v_pk_fma_f32 v[188:189], v[60:61], s[68:69], v[50:51] op_sel_hi:[1,0,1]
	ds_read_b32 v48, v48
	ds_read_b32 v50, v0
	v_subrev_u32_e32 v0, 27, v226
	v_med3_i32 v49, v0, 0, v201
	v_med3_i32 v0, v0, 32, v202
	v_lshl_add_u32 v0, v0, 2, s91
	v_lshl_add_u32 v49, v49, 2, s91
	v_add_u32_e32 v0, 0xffffff80, v0
	ds_read_b32 v49, v49
	ds_read_b32 v51, v0
	v_pk_fma_f32 v[10:11], v[68:69], s[68:69], v[10:11] op_sel_hi:[1,0,1]
	v_pk_fma_f32 v[12:13], v[52:53], s[68:69], v[12:13] op_sel_hi:[1,0,1]
	v_pk_fma_f32 v[14:15], v[70:71], s[68:69], v[14:15] op_sel_hi:[1,0,1]
	s_waitcnt lgkmcnt(1)
	v_pk_fma_f32 v[190:191], v[78:79], s[68:69], v[48:49] op_sel_hi:[1,0,1]
	s_waitcnt lgkmcnt(0)
	v_pk_fma_f32 v[192:193], v[62:63], s[68:69], v[50:51] op_sel_hi:[1,0,1]
